# attention fast path back-edge rotated: loop bookkeeping and K base before the tile barrier, K-fragment LDS reads first after it, next-tile global loads after them
# baseline (speedup 1.0000x reference)
; #define LAS __attribute__((address_space(3)))
; #define LDS_WAIT() asm volatile("s_waitcnt lgkmcnt(0)" ::: "memory")
; __device__ __forceinline__ float shx(float v, int mask, int lane) { return __int_as_float(__builtin_amdgcn_ds_bpermute((lane ^ mask) << 2, __float_as_int(v))); }
; __device__ __forceinline__ int crow(int r, int hi) { return (r & 3) + 8 * (r >> 2) + 4 * hi; }
; __device__ __forceinline__ void phase_attn(const Params& p, int S, int lgS, int B, int* counter, LAS unsigned char* lds) {
;     ...
;             f32x16 pp[4] = {negm, negm, negm, negm};
;             const LAS unsigned char* kl = kb + klane; const LAS unsigned char* vl = vb + vlane;
; #pragma unroll
;             for (int d0 = 0; d0 < 4; ++d0)
; #pragma unroll
;                 for (int j = 0; j < 4; ++j) { const bf16x8 a = *(const LAS bf16x8*)(kl + (32 * j * 72 + 16 * d0) * 2); pp[j] = __builtin_amdgcn_mfma_f32_32x32x16_bf16(a, qr[d0], pp[j], 0, 0, 0); }
;             float mxa = fmaxf(pp[0][0], pp[1][0]), mxb = fmaxf(pp[2][0], pp[3][0]);
; #pragma unroll
;             for (int r = 1; r < 16; ++r) { mxa = fmaxf(fmaxf(mxa, pp[0][r]), pp[1][r]); mxb = fmaxf(fmaxf(mxb, pp[2][r]), pp[3][r]); }
;             float mx = fmaxf(mxa, mxb);
;             mx = fmaxf(mx, shx(mx, 32, lane));
;             const bool first = (t == 0);
;             if (first || __any(mx > 8.f)) {
;                 const float d = first ? mx : fmaxf(mx, 0.f);
;                 m_run += d;
; #pragma unroll
;                 for (int j = 0; j < 4; ++j)
; #pragma unroll
;                     for (int r = 0; r < 16; ++r) pp[j][r] -= d;
; #pragma unroll
;                 for (int r = 0; r < 16; ++r) negm[r] = -m_run;
;                 if (!first) {
;                     const float alpha = __builtin_amdgcn_exp2f(-d); l_run *= alpha;
;                     if (hi == 0) wsf[r32] = alpha;
;                     LDS_WAIT();
; #pragma unroll
;                     for (int r = 0; r < 16; ++r) { const float f = wsf[crow(r, hi)]; o0[r] *= f; o1[r] *= f; }
;                     LDS_WAIT();
;                 }
;             }
;             float ls = 0.f;
; #pragma unroll
;             for (int j = 0; j < 4; ++j)
; #pragma unroll
;                 for (int r = 0; r < 16; ++r) { pp[j][r] = __builtin_amdgcn_exp2f(pp[j][r]); ls += pp[j][r]; }
;             l_run += ls;
.Latt_fast_body:
	s_mov_b32 s19, 0x43800000
	s_waitcnt lgkmcnt(3)
	v_mfma_f32_32x32x16_bf16 v[96:111], v[224:227], v[112:115], v[32:47]
	ds_read_b128 v[224:227], v155 offset:32
	s_waitcnt lgkmcnt(3)
	v_mfma_f32_32x32x16_bf16 v[80:95], v[228:231], v[112:115], v[32:47]
	ds_read_b128 v[228:231], v155 offset:4640
	s_waitcnt lgkmcnt(3)
	v_mfma_f32_32x32x16_bf16 v[64:79], v[232:235], v[112:115], v[32:47]
	ds_read_b128 v[232:235], v155 offset:9248
	s_waitcnt lgkmcnt(3)
	v_mfma_f32_32x32x16_bf16 v[48:63], v[242:245], v[112:115], v[32:47]
	ds_read_b128 v[242:245], v155 offset:13856
	s_waitcnt lgkmcnt(3)
	v_mfma_f32_32x32x16_bf16 v[96:111], v[224:227], v[116:119], v[96:111]
	ds_read_b128 v[224:227], v155 offset:64
	s_waitcnt lgkmcnt(3)
	v_mfma_f32_32x32x16_bf16 v[80:95], v[228:231], v[116:119], v[80:95]
	ds_read_b128 v[228:231], v155 offset:4672
	s_waitcnt lgkmcnt(3)
	v_mfma_f32_32x32x16_bf16 v[64:79], v[232:235], v[116:119], v[64:79]
	ds_read_b128 v[232:235], v155 offset:9280
	s_waitcnt lgkmcnt(3)
	v_mfma_f32_32x32x16_bf16 v[48:63], v[242:245], v[116:119], v[48:63]
	ds_read_b128 v[242:245], v155 offset:13888
	s_waitcnt lgkmcnt(3)
	v_mfma_f32_32x32x16_bf16 v[96:111], v[224:227], v[120:123], v[96:111]
	ds_read_b128 v[224:227], v155 offset:96
	s_waitcnt lgkmcnt(3)
	v_mfma_f32_32x32x16_bf16 v[80:95], v[228:231], v[120:123], v[80:95]
	ds_read_b128 v[228:231], v155 offset:4704
	s_waitcnt lgkmcnt(3)
	v_mfma_f32_32x32x16_bf16 v[64:79], v[232:235], v[120:123], v[64:79]
	ds_read_b128 v[232:235], v155 offset:9312
	s_waitcnt lgkmcnt(3)
	v_mfma_f32_32x32x16_bf16 v[48:63], v[242:245], v[120:123], v[48:63]
	ds_read_b128 v[242:245], v155 offset:13920
	s_waitcnt lgkmcnt(3)
	v_mfma_f32_32x32x16_bf16 v[96:111], v[224:227], v[124:127], v[96:111]
	s_waitcnt lgkmcnt(2)
	v_mfma_f32_32x32x16_bf16 v[80:95], v[228:231], v[124:127], v[80:95]
	s_waitcnt lgkmcnt(1)
	v_mfma_f32_32x32x16_bf16 v[64:79], v[232:235], v[124:127], v[64:79]
	s_waitcnt lgkmcnt(0)
	v_mfma_f32_32x32x16_bf16 v[48:63], v[242:245], v[124:127], v[48:63]
	v_add3_u32 v155, s18, v186, v199
	v_add_u32_e32 v157, 0x4800, v155
	v_add_u32_e32 v155, 0x6800, v155
	ds_read_b128 v[228:231], v157
	ds_read_b128 v[232:235], v155 offset:512
	ds_read_b128 v[242:245], v157 offset:32
	s_nop 0
	v_exp_f32_e32 v96, v96
	v_exp_f32_e32 v97, v97
	v_exp_f32_e32 v98, v98
	v_exp_f32_e32 v99, v99
	v_exp_f32_e32 v100, v100
	v_exp_f32_e32 v101, v101
	v_exp_f32_e32 v102, v102
	v_exp_f32_e32 v103, v103
	v_exp_f32_e32 v104, v104
	v_exp_f32_e32 v105, v105
	v_exp_f32_e32 v106, v106
	v_exp_f32_e32 v107, v107
	v_exp_f32_e32 v108, v108
	v_exp_f32_e32 v109, v109
	v_exp_f32_e32 v110, v110
	v_exp_f32_e32 v111, v111
	v_exp_f32_e32 v80, v80
	v_exp_f32_e32 v81, v81
	v_exp_f32_e32 v82, v82
	v_exp_f32_e32 v83, v83
	v_exp_f32_e32 v84, v84
	v_exp_f32_e32 v85, v85
	v_exp_f32_e32 v86, v86
	v_exp_f32_e32 v87, v87
	v_exp_f32_e32 v88, v88
	v_exp_f32_e32 v89, v89
	v_exp_f32_e32 v90, v90
	v_exp_f32_e32 v91, v91
	v_exp_f32_e32 v92, v92
	v_exp_f32_e32 v93, v93
	v_exp_f32_e32 v94, v94
	v_exp_f32_e32 v95, v95
	v_exp_f32_e32 v64, v64
	v_exp_f32_e32 v65, v65
	v_exp_f32_e32 v66, v66
	v_exp_f32_e32 v67, v67
	v_exp_f32_e32 v68, v68
	v_exp_f32_e32 v69, v69
	v_exp_f32_e32 v70, v70
	v_exp_f32_e32 v71, v71
	v_exp_f32_e32 v72, v72
	v_exp_f32_e32 v73, v73
	v_exp_f32_e32 v74, v74
	v_exp_f32_e32 v75, v75
	v_exp_f32_e32 v76, v76
	v_exp_f32_e32 v77, v77
	v_exp_f32_e32 v78, v78
	v_exp_f32_e32 v79, v79
	v_exp_f32_e32 v48, v48
	v_exp_f32_e32 v49, v49
	v_exp_f32_e32 v50, v50
	v_exp_f32_e32 v51, v51
	v_exp_f32_e32 v52, v52
	v_exp_f32_e32 v53, v53
	v_exp_f32_e32 v54, v54
	v_exp_f32_e32 v55, v55
	v_exp_f32_e32 v56, v56
	v_exp_f32_e32 v57, v57
	v_exp_f32_e32 v58, v58
	v_exp_f32_e32 v59, v59
	v_exp_f32_e32 v60, v60
	v_exp_f32_e32 v61, v61
	v_exp_f32_e32 v62, v62
	v_exp_f32_e32 v63, v63
	v_add_f32_e32 v236, v97, v96
	v_add_f32_e32 v236, v98, v236
	v_add_f32_e32 v236, v99, v236
	v_add_f32_e32 v236, v100, v236
	v_add_f32_e32 v236, v101, v236
	v_add_f32_e32 v236, v102, v236
	v_add_f32_e32 v236, v103, v236
	v_add_f32_e32 v236, v104, v236
	v_add_f32_e32 v236, v105, v236
	v_add_f32_e32 v236, v106, v236
	v_add_f32_e32 v236, v107, v236
	v_add_f32_e32 v236, v108, v236
	v_add_f32_e32 v236, v109, v236
	v_add_f32_e32 v236, v110, v236
	v_add_f32_e32 v236, v111, v236
	v_add_f32_e32 v236, v80, v236
	v_add_f32_e32 v236, v81, v236
	v_add_f32_e32 v236, v82, v236
	v_add_f32_e32 v236, v83, v236
	v_add_f32_e32 v236, v84, v236
	v_add_f32_e32 v236, v85, v236
	v_add_f32_e32 v236, v86, v236
	v_add_f32_e32 v236, v87, v236
	v_add_f32_e32 v236, v88, v236
	v_add_f32_e32 v236, v89, v236
	v_add_f32_e32 v236, v90, v236
	v_add_f32_e32 v236, v91, v236
	v_add_f32_e32 v236, v92, v236
	v_add_f32_e32 v236, v93, v236
	v_add_f32_e32 v236, v94, v236
	v_add_f32_e32 v236, v95, v236
	v_add_f32_e32 v236, v64, v236
	v_add_f32_e32 v236, v65, v236
	v_add_f32_e32 v236, v66, v236
	v_add_f32_e32 v236, v67, v236
	v_add_f32_e32 v236, v68, v236
	v_add_f32_e32 v236, v69, v236
	v_add_f32_e32 v236, v70, v236
	v_add_f32_e32 v236, v71, v236
	v_add_f32_e32 v236, v72, v236
	v_add_f32_e32 v236, v73, v236
	v_add_f32_e32 v236, v74, v236
	v_add_f32_e32 v236, v75, v236
	v_add_f32_e32 v236, v76, v236
	v_add_f32_e32 v236, v77, v236
	v_add_f32_e32 v236, v78, v236
	v_add_f32_e32 v236, v79, v236
	v_add_f32_e32 v236, v48, v236
	v_add_f32_e32 v236, v49, v236
	v_add_f32_e32 v236, v50, v236
	v_add_f32_e32 v236, v51, v236
	v_add_f32_e32 v236, v52, v236
	v_add_f32_e32 v236, v53, v236
	v_add_f32_e32 v236, v54, v236
	v_add_f32_e32 v236, v55, v236
	v_add_f32_e32 v236, v56, v236
	v_add_f32_e32 v236, v57, v236
	v_add_f32_e32 v236, v58, v236
	v_add_f32_e32 v236, v59, v236
	v_add_f32_e32 v236, v60, v236
	v_add_f32_e32 v236, v61, v236
	v_add_f32_e32 v236, v62, v236
	v_add_f32_e32 v236, v63, v236
	v_cmp_lt_f32_e32 vcc, s19, v236
	s_cbranch_vccnz .Latt_slow
; #define LAS __attribute__((address_space(3)))
; __device__ __forceinline__ void phase_attn(const Params& p, int S, int lgS, int B, int* counter, LAS unsigned char* lds) {
;     ...
;         for (int t = 0; t < NT; ++t) {
;             const LAS unsigned char* kb = lds + (t & 1) * BUFB; const LAS unsigned char* vb = kb + KB;
;             if (t + 1 < NT) { const bf16_t* kn = ksrc + (size_t)(t + 1) * 128 * 2048; const bf16_t* vn_ = vsrc + (t + 1) * 128;
;                 kreg0 = *(const u32x4*)kn; kreg1 = *(const u32x4*)(kn + (size_t)64 * 2048); vreg0 = *(const u32x4*)vn_; vreg1 = *(const u32x4*)(vn_ + 64); }
;     ...
;             l_run += ls;
; #pragma unroll
;             for (int j = 0; j < 4; ++j)
; #pragma unroll
;                 for (int kk = 0; kk < 2; ++kk) {
;                     const int ks = 2 * j + kk;
;                     const bf16x8 pa = pack8(pp[j][8 * kk], pp[j][8 * kk + 1], pp[j][8 * kk + 2], pp[j][8 * kk + 3], pp[j][8 * kk + 4], pp[j][8 * kk + 5], pp[j][8 * kk + 6], pp[j][8 * kk + 7]);
;                     const u32x2 v0a = *(const LAS u32x2*)(vl + (16 * ks) * 2), v0b = *(const LAS u32x2*)(vl + (16 * ks + 8) * 2);
;                     const u32x2 v1a = *(const LAS u32x2*)(vl + (32 * 136 + 16 * ks) * 2), v1b = *(const LAS u32x2*)(vl + (32 * 136 + 16 * ks + 8) * 2);
;                     const u32x4 f0 = {v0a.x, v0a.y, v0b.x, v0b.y}, f1 = {v1a.x, v1a.y, v1b.x, v1b.y};
;                     o0 = __builtin_amdgcn_mfma_f32_32x32x16_bf16(pa, __builtin_bit_cast(bf16x8, f0), o0, 0, 0, 0);
;                     o1 = __builtin_amdgcn_mfma_f32_32x32x16_bf16(pa, __builtin_bit_cast(bf16x8, f1), o1, 0, 0, 0);
;                 }
;             if (t + 1 < NT) { LAS unsigned char* nb = lds + ((t + 1) & 1) * BUFB;
;                 *(LAS u32x4*)(nb + kdst) = kreg0; *(LAS u32x4*)(nb + kdst + 64 * 144) = kreg1; *(LAS u32x4*)(nb + vdst) = vreg0; *(LAS u32x4*)(nb + vdst + 128) = vreg1; }
;             __syncthreads();
;         }
	v_cvt_pk_bf16_f32 v224, v96, v97
	v_cvt_pk_bf16_f32 v225, v98, v99
	v_cvt_pk_bf16_f32 v226, v100, v101
	v_cvt_pk_bf16_f32 v227, v102, v103
	v_add_f32_e32 v195, v195, v236
	s_waitcnt lgkmcnt(1)
	v_mfma_f32_32x32x16_bf16 v[0:15], v[224:227], v[228:231], v[0:15]
	ds_read_b128 v[228:231], v155 offset:544
	v_mfma_f32_32x32x16_bf16 v[16:31], v[224:227], v[232:235], v[16:31]
	v_cvt_pk_bf16_f32 v224, v104, v105
	v_cvt_pk_bf16_f32 v225, v106, v107
	v_cvt_pk_bf16_f32 v226, v108, v109
	v_cvt_pk_bf16_f32 v227, v110, v111
	ds_read_b128 v[232:235], v157 offset:64
	s_waitcnt lgkmcnt(1)
	v_mfma_f32_32x32x16_bf16 v[0:15], v[224:227], v[242:245], v[0:15]
	ds_read_b128 v[242:245], v155 offset:576
	v_mfma_f32_32x32x16_bf16 v[16:31], v[224:227], v[228:231], v[16:31]
	v_cvt_pk_bf16_f32 v224, v80, v81
	v_cvt_pk_bf16_f32 v225, v82, v83
	v_cvt_pk_bf16_f32 v226, v84, v85
	v_cvt_pk_bf16_f32 v227, v86, v87
	ds_read_b128 v[228:231], v157 offset:96
	s_waitcnt lgkmcnt(1)
	v_mfma_f32_32x32x16_bf16 v[0:15], v[224:227], v[232:235], v[0:15]
	ds_read_b128 v[232:235], v155 offset:608
	v_mfma_f32_32x32x16_bf16 v[16:31], v[224:227], v[242:245], v[16:31]
	v_cvt_pk_bf16_f32 v224, v88, v89
	v_cvt_pk_bf16_f32 v225, v90, v91
	v_cvt_pk_bf16_f32 v226, v92, v93
	v_cvt_pk_bf16_f32 v227, v94, v95
	ds_read_b128 v[242:245], v157 offset:128
	s_waitcnt lgkmcnt(1)
	v_mfma_f32_32x32x16_bf16 v[0:15], v[224:227], v[228:231], v[0:15]
	ds_read_b128 v[228:231], v155 offset:640
	v_mfma_f32_32x32x16_bf16 v[16:31], v[224:227], v[232:235], v[16:31]
	v_cvt_pk_bf16_f32 v224, v64, v65
	v_cvt_pk_bf16_f32 v225, v66, v67
	v_cvt_pk_bf16_f32 v226, v68, v69
	v_cvt_pk_bf16_f32 v227, v70, v71
	ds_read_b128 v[232:235], v157 offset:160
	s_waitcnt lgkmcnt(1)
	v_mfma_f32_32x32x16_bf16 v[0:15], v[224:227], v[242:245], v[0:15]
	ds_read_b128 v[242:245], v155 offset:672
	v_mfma_f32_32x32x16_bf16 v[16:31], v[224:227], v[228:231], v[16:31]
	v_cvt_pk_bf16_f32 v224, v72, v73
	v_cvt_pk_bf16_f32 v225, v74, v75
	v_cvt_pk_bf16_f32 v226, v76, v77
	v_cvt_pk_bf16_f32 v227, v78, v79
	ds_read_b128 v[228:231], v157 offset:192
	s_waitcnt lgkmcnt(1)
	v_mfma_f32_32x32x16_bf16 v[0:15], v[224:227], v[232:235], v[0:15]
	ds_read_b128 v[232:235], v155 offset:704
	v_mfma_f32_32x32x16_bf16 v[16:31], v[224:227], v[242:245], v[16:31]
	v_cvt_pk_bf16_f32 v224, v48, v49
	v_cvt_pk_bf16_f32 v225, v50, v51
	v_cvt_pk_bf16_f32 v226, v52, v53
	v_cvt_pk_bf16_f32 v227, v54, v55
	ds_read_b128 v[242:245], v157 offset:224
	s_waitcnt lgkmcnt(1)
	v_mfma_f32_32x32x16_bf16 v[0:15], v[224:227], v[228:231], v[0:15]
	ds_read_b128 v[228:231], v155 offset:736
	v_mfma_f32_32x32x16_bf16 v[16:31], v[224:227], v[232:235], v[16:31]
	v_cvt_pk_bf16_f32 v224, v56, v57
	v_cvt_pk_bf16_f32 v225, v58, v59
	v_cvt_pk_bf16_f32 v226, v60, v61
	v_cvt_pk_bf16_f32 v227, v62, v63
	s_andn2_b64 vcc, exec, s[26:27]
	s_waitcnt lgkmcnt(0)
	v_mfma_f32_32x32x16_bf16 v[0:15], v[224:227], v[242:245], v[0:15]
	v_mfma_f32_32x32x16_bf16 v[16:31], v[224:227], v[228:231], v[16:31]
	s_cbranch_vccnz .Latt_fast_nowr
	s_bitcmp1_b32 s17, 0
	s_cselect_b32 s18, 0x8c00, 0
	v_add_u32_e32 v155, s18, v145
	v_add_u32_e32 v157, s18, v149
	s_waitcnt vmcnt(3)
	ds_write_b128 v155, v[128:131]
	s_waitcnt vmcnt(2)
	ds_write_b128 v155, v[132:135] offset:9216
	s_waitcnt vmcnt(1)
	ds_write2_b64 v157, v[136:137], v[138:139] offset1:2
	s_waitcnt vmcnt(0)
	ds_write2_b64 v157, v[140:141], v[142:143] offset0:16 offset1:18
.Latt_fast_nowr:
	s_addk_i32 s96, 0x80
	s_add_u32 s22, s22, 0x80000
	s_addc_u32 s23, s23, 0
	s_add_u32 s24, s24, 0x80000
	s_addc_u32 s25, s25, 0
	s_add_u32 s28, s28, 0x100
	s_addc_u32 s29, s29, 0
	s_cmp_eq_u32 s93, s17
	s_cbranch_scc1 .Latt_fast_exit
	s_mov_b32 s18, s17
	s_add_i32 s17, s18, 1
	s_cmp_lt_u32 s17, s93
	s_cselect_b64 s[26:27], -1, 0
	s_bitcmp1_b32 s18, 0
	s_cselect_b32 s18, 0x8c00, 0
	v_add_u32_e32 v155, s18, v198
	s_andn2_b64 vcc, exec, s[26:27]
	s_waitcnt lgkmcnt(0)
	s_barrier
	ds_read_b128 v[224:227], v155
	ds_read_b128 v[228:231], v155 offset:4608
	ds_read_b128 v[232:235], v155 offset:9216
	ds_read_b128 v[242:245], v155 offset:13824
	s_cbranch_vccnz .Latt_fast_body
	global_load_dwordx4 v[128:131], v239, s[24:25]
	global_load_dwordx4 v[132:135], v239, s[22:23]
	global_load_dwordx4 v[136:139], v238, s[28:29]
	global_load_dwordx4 v[140:143], v238, s[28:29] offset:128
	s_branch .Latt_fast_body
.Latt_fast_exit:
	s_waitcnt lgkmcnt(0)
	s_barrier
	s_branch .LBB0_739
